# grid barrier: non-leader workgroups wait on the global generation word instead of their XCD generation word (one hop less on every barrier release)
# speedup vs baseline: 1.0141x; 1.0054x over previous
; __device__ __forceinline__ unsigned xb_ld(unsigned* p)              { return __hip_atomic_load(p, __ATOMIC_RELAXED, __HIP_MEMORY_SCOPE_AGENT); }
; __device__ __forceinline__ unsigned xb_add(unsigned* p, unsigned v) { return __hip_atomic_fetch_add(p, v, __ATOMIC_RELAXED, __HIP_MEMORY_SCOPE_AGENT); }
; #define XB_SPIN(cond, bar) do { unsigned _sp = 0; while (cond) { if (XB_SLEEP) __builtin_amdgcn_s_sleep(1); \
;     if ((++_sp & 255u) == 0u) { if (xb_ld(&(bar)[XB_TMO])) break; if (_sp > XB_SPIN_CAP) { atomicAdd(&(bar)[XB_TMO], 1u); break; } } } } while (0)
; __device__ __forceinline__ void xcd_barrier(const XcdBarrier& b) {
;     ...
;         const unsigned old = xb_add(&bar[XB_XSUB(b.x)], 1u);
;         const unsigned gen = old / nloc;
;         if (old + 1u == (gen + 1u) * nloc) {
;             __builtin_amdgcn_fence(__ATOMIC_RELEASE, "agent");
;             asm volatile("s_waitcnt vmcnt(0)" ::: "memory");
;             const unsigned og = xb_add(&bar[XB_TOP], 1u);
;             const unsigned tg = og / nx;
;             if (og + 1u == (tg + 1u) * nx) xb_add(&bar[XB_TOPGEN], 1u);
;             else XB_SPIN(xb_ld(&bar[XB_TOPGEN]) == tg, bar);
;             __builtin_amdgcn_fence(__ATOMIC_ACQUIRE, "agent");
;             xb_add(&bar[XB_XGEN(b.x)], 1u);
;             asm volatile("s_waitcnt vmcnt(0)" ::: "memory");
;         } else {
;             XB_SPIN(xb_ld(&bar[XB_XGEN(b.x)]) == gen, bar);
;             __builtin_amdgcn_fence(__ATOMIC_ACQUIRE, "agent");
;             asm volatile("s_waitcnt vmcnt(0)" ::: "memory");
.LBB0_100:
	s_or_b64 exec, exec, s[24:25]
	v_cvt_f32_u32_e32 v4, v2
	s_waitcnt vmcnt(0)
	v_readfirstlane_b32 s19, v3
	v_sub_u32_e32 v3, 0, v2
	v_rcp_iflag_f32_e32 v4, v4
	v_add_u32_e32 v5, s19, v1
	v_mul_f32_e32 v4, 0x4f7ffffe, v4
	v_cvt_u32_f32_e32 v4, v4
	v_mul_lo_u32 v1, v3, v4
	v_mul_hi_u32 v1, v4, v1
	v_add_u32_e32 v1, v4, v1
	v_mul_hi_u32 v1, v5, v1
	v_mul_lo_u32 v3, v1, v2
	v_sub_u32_e32 v3, v5, v3
	v_add_u32_e32 v4, 1, v1
	v_cmp_ge_u32_e32 vcc, v3, v2
	s_nop 1
	v_cndmask_b32_e32 v1, v1, v4, vcc
	v_sub_u32_e32 v4, v3, v2
	v_cndmask_b32_e32 v3, v3, v4, vcc
	v_add_u32_e32 v4, 1, v1
	v_cmp_ge_u32_e32 vcc, v3, v2
	v_add_u32_e32 v3, 1, v5
	s_nop 0
	v_cndmask_b32_e32 v1, v1, v4, vcc
	v_mul_lo_u32 v4, v2, v1
	v_add_u32_e32 v2, v4, v2
	v_cmp_ne_u32_e32 vcc, v3, v2
	s_and_saveexec_b64 s[22:23], vcc
	s_xor_b64 s[22:23], exec, s[22:23]
	s_cbranch_execz .LBB0_114
	s_waitcnt lgkmcnt(0)
	s_add_u32 s30, s86, 0x3500
	s_addc_u32 s31, s87, 0
	v_mov_b32_e32 v0, 0
	global_load_dword v0, v0, s[30:31] sc1
	s_waitcnt vmcnt(0)
	v_cmp_eq_u32_e32 vcc, v0, v1
	s_and_saveexec_b64 s[24:25], vcc
	s_cbranch_execz .LBB0_113
	s_add_u32 s26, s80, 0x60200
	s_addc_u32 s27, s81, 0
	s_mov_b32 s19, 1
	s_mov_b64 s[34:35], 0
	v_mov_b32_e32 v0, 0
	s_branch .LBB0_104

; __device__ __forceinline__ unsigned xb_ld(unsigned* p)              { return __hip_atomic_load(p, __ATOMIC_RELAXED, __HIP_MEMORY_SCOPE_AGENT); }
; __device__ __forceinline__ unsigned xb_add(unsigned* p, unsigned v) { return __hip_atomic_fetch_add(p, v, __ATOMIC_RELAXED, __HIP_MEMORY_SCOPE_AGENT); }
; #define XB_SPIN(cond, bar) do { unsigned _sp = 0; while (cond) { if (XB_SLEEP) __builtin_amdgcn_s_sleep(1); \
;     if ((++_sp & 255u) == 0u) { if (xb_ld(&(bar)[XB_TMO])) break; if (_sp > XB_SPIN_CAP) { atomicAdd(&(bar)[XB_TMO], 1u); break; } } } } while (0)
; __device__ __forceinline__ void xcd_barrier(const XcdBarrier& b) {
;     ...
;         const unsigned old = xb_add(&bar[XB_XSUB(b.x)], 1u);
;         const unsigned gen = old / nloc;
;         if (old + 1u == (gen + 1u) * nloc) {
;             __builtin_amdgcn_fence(__ATOMIC_RELEASE, "agent");
;             asm volatile("s_waitcnt vmcnt(0)" ::: "memory");
;             const unsigned og = xb_add(&bar[XB_TOP], 1u);
;             const unsigned tg = og / nx;
;             if (og + 1u == (tg + 1u) * nx) xb_add(&bar[XB_TOPGEN], 1u);
;             else XB_SPIN(xb_ld(&bar[XB_TOPGEN]) == tg, bar);
;             __builtin_amdgcn_fence(__ATOMIC_ACQUIRE, "agent");
;             xb_add(&bar[XB_XGEN(b.x)], 1u);
;             asm volatile("s_waitcnt vmcnt(0)" ::: "memory");
;         } else {
;             XB_SPIN(xb_ld(&bar[XB_XGEN(b.x)]) == gen, bar);
;             __builtin_amdgcn_fence(__ATOMIC_ACQUIRE, "agent");
;             asm volatile("s_waitcnt vmcnt(0)" ::: "memory");
.LBB0_183:
	s_or_b64 exec, exec, s[20:21]
	v_cvt_f32_u32_e32 v4, v2
	s_waitcnt vmcnt(0)
	v_readfirstlane_b32 s18, v3
	v_sub_u32_e32 v3, 0, v2
	v_rcp_iflag_f32_e32 v4, v4
	v_add_u32_e32 v5, s18, v1
	v_mul_f32_e32 v4, 0x4f7ffffe, v4
	v_cvt_u32_f32_e32 v4, v4
	v_mul_lo_u32 v1, v3, v4
	v_mul_hi_u32 v1, v4, v1
	v_add_u32_e32 v1, v4, v1
	v_mul_hi_u32 v1, v5, v1
	v_mul_lo_u32 v3, v1, v2
	v_sub_u32_e32 v3, v5, v3
	v_add_u32_e32 v4, 1, v1
	v_cmp_ge_u32_e32 vcc, v3, v2
	s_nop 1
	v_cndmask_b32_e32 v1, v1, v4, vcc
	v_sub_u32_e32 v4, v3, v2
	v_cndmask_b32_e32 v3, v3, v4, vcc
	v_add_u32_e32 v4, 1, v1
	v_cmp_ge_u32_e32 vcc, v3, v2
	v_add_u32_e32 v3, 1, v5
	s_nop 0
	v_cndmask_b32_e32 v1, v1, v4, vcc
	v_mul_lo_u32 v4, v2, v1
	v_add_u32_e32 v2, v4, v2
	v_cmp_ne_u32_e32 vcc, v3, v2
	s_and_saveexec_b64 s[18:19], vcc
	s_xor_b64 s[18:19], exec, s[18:19]
	s_cbranch_execz .LBB0_197
	s_waitcnt lgkmcnt(0)
	s_add_u32 s24, s86, 0x3500
	s_addc_u32 s25, s87, 0
	v_mov_b32_e32 v0, 0
	global_load_dword v0, v0, s[24:25] sc1
	s_waitcnt vmcnt(0)
	v_cmp_eq_u32_e32 vcc, v0, v1
	s_and_saveexec_b64 s[20:21], vcc
	s_cbranch_execz .LBB0_196
	s_add_u32 s22, s80, 0x60200
	s_addc_u32 s23, s81, 0
	s_mov_b32 s33, 1
	s_mov_b64 s[26:27], 0
	v_mov_b32_e32 v0, 0
	s_branch .LBB0_187

; __device__ __forceinline__ unsigned xb_ld(unsigned* p)              { return __hip_atomic_load(p, __ATOMIC_RELAXED, __HIP_MEMORY_SCOPE_AGENT); }
; __device__ __forceinline__ unsigned xb_add(unsigned* p, unsigned v) { return __hip_atomic_fetch_add(p, v, __ATOMIC_RELAXED, __HIP_MEMORY_SCOPE_AGENT); }
; #define XB_SPIN(cond, bar) do { unsigned _sp = 0; while (cond) { if (XB_SLEEP) __builtin_amdgcn_s_sleep(1); \
;     if ((++_sp & 255u) == 0u) { if (xb_ld(&(bar)[XB_TMO])) break; if (_sp > XB_SPIN_CAP) { atomicAdd(&(bar)[XB_TMO], 1u); break; } } } } while (0)
; __device__ __forceinline__ void xcd_barrier(const XcdBarrier& b) {
;     ...
;         const unsigned old = xb_add(&bar[XB_XSUB(b.x)], 1u);
;         const unsigned gen = old / nloc;
;         if (old + 1u == (gen + 1u) * nloc) {
;             __builtin_amdgcn_fence(__ATOMIC_RELEASE, "agent");
;             asm volatile("s_waitcnt vmcnt(0)" ::: "memory");
;             const unsigned og = xb_add(&bar[XB_TOP], 1u);
;             const unsigned tg = og / nx;
;             if (og + 1u == (tg + 1u) * nx) xb_add(&bar[XB_TOPGEN], 1u);
;             else XB_SPIN(xb_ld(&bar[XB_TOPGEN]) == tg, bar);
;             __builtin_amdgcn_fence(__ATOMIC_ACQUIRE, "agent");
;             xb_add(&bar[XB_XGEN(b.x)], 1u);
;             asm volatile("s_waitcnt vmcnt(0)" ::: "memory");
;         } else {
;             XB_SPIN(xb_ld(&bar[XB_XGEN(b.x)]) == gen, bar);
;             __builtin_amdgcn_fence(__ATOMIC_ACQUIRE, "agent");
;             asm volatile("s_waitcnt vmcnt(0)" ::: "memory");
.LBB0_254:
	s_or_b64 exec, exec, s[18:19]
	v_cvt_f32_u32_e32 v4, v2
	s_waitcnt vmcnt(0)
	v_readfirstlane_b32 s14, v3
	v_sub_u32_e32 v3, 0, v2
	v_rcp_iflag_f32_e32 v4, v4
	v_add_u32_e32 v5, s14, v1
	v_mul_f32_e32 v4, 0x4f7ffffe, v4
	v_cvt_u32_f32_e32 v4, v4
	v_mul_lo_u32 v1, v3, v4
	v_mul_hi_u32 v1, v4, v1
	v_add_u32_e32 v1, v4, v1
	v_mul_hi_u32 v1, v5, v1
	v_mul_lo_u32 v3, v1, v2
	v_sub_u32_e32 v3, v5, v3
	v_add_u32_e32 v4, 1, v1
	v_cmp_ge_u32_e32 vcc, v3, v2
	s_nop 1
	v_cndmask_b32_e32 v1, v1, v4, vcc
	v_sub_u32_e32 v4, v3, v2
	v_cndmask_b32_e32 v3, v3, v4, vcc
	v_add_u32_e32 v4, 1, v1
	v_cmp_ge_u32_e32 vcc, v3, v2
	v_add_u32_e32 v3, 1, v5
	s_nop 0
	v_cndmask_b32_e32 v1, v1, v4, vcc
	v_mul_lo_u32 v4, v2, v1
	v_add_u32_e32 v2, v4, v2
	v_cmp_ne_u32_e32 vcc, v3, v2
	s_and_saveexec_b64 s[14:15], vcc
	s_xor_b64 s[14:15], exec, s[14:15]
	s_cbranch_execz .LBB0_268
	s_waitcnt lgkmcnt(0)
	s_add_u32 s22, s86, 0x3500
	s_addc_u32 s23, s87, 0
	v_mov_b32_e32 v0, 0
	global_load_dword v0, v0, s[22:23] sc1
	s_waitcnt vmcnt(0)
	v_cmp_eq_u32_e32 vcc, v0, v1
	s_and_saveexec_b64 s[18:19], vcc
	s_cbranch_execz .LBB0_267
	s_add_u32 s20, s80, 0x60200
	s_addc_u32 s21, s81, 0
	s_mov_b32 s33, 1
	s_mov_b64 s[24:25], 0
	v_mov_b32_e32 v0, 0
	s_branch .LBB0_258

; __device__ __forceinline__ unsigned xb_ld(unsigned* p)              { return __hip_atomic_load(p, __ATOMIC_RELAXED, __HIP_MEMORY_SCOPE_AGENT); }
; __device__ __forceinline__ unsigned xb_add(unsigned* p, unsigned v) { return __hip_atomic_fetch_add(p, v, __ATOMIC_RELAXED, __HIP_MEMORY_SCOPE_AGENT); }
; #define XB_SPIN(cond, bar) do { unsigned _sp = 0; while (cond) { if (XB_SLEEP) __builtin_amdgcn_s_sleep(1); \
;     if ((++_sp & 255u) == 0u) { if (xb_ld(&(bar)[XB_TMO])) break; if (_sp > XB_SPIN_CAP) { atomicAdd(&(bar)[XB_TMO], 1u); break; } } } } while (0)
; __device__ __forceinline__ void xcd_barrier(const XcdBarrier& b) {
;     ...
;         const unsigned old = xb_add(&bar[XB_XSUB(b.x)], 1u);
;         const unsigned gen = old / nloc;
;         if (old + 1u == (gen + 1u) * nloc) {
;             __builtin_amdgcn_fence(__ATOMIC_RELEASE, "agent");
;             asm volatile("s_waitcnt vmcnt(0)" ::: "memory");
;             const unsigned og = xb_add(&bar[XB_TOP], 1u);
;             const unsigned tg = og / nx;
;             if (og + 1u == (tg + 1u) * nx) xb_add(&bar[XB_TOPGEN], 1u);
;             else XB_SPIN(xb_ld(&bar[XB_TOPGEN]) == tg, bar);
;             __builtin_amdgcn_fence(__ATOMIC_ACQUIRE, "agent");
;             xb_add(&bar[XB_XGEN(b.x)], 1u);
;             asm volatile("s_waitcnt vmcnt(0)" ::: "memory");
;         } else {
;             XB_SPIN(xb_ld(&bar[XB_XGEN(b.x)]) == gen, bar);
;             __builtin_amdgcn_fence(__ATOMIC_ACQUIRE, "agent");
;             asm volatile("s_waitcnt vmcnt(0)" ::: "memory");
.LBB0_368:
	s_or_b64 exec, exec, s[16:17]
	v_cvt_f32_u32_e32 v4, v2
	s_waitcnt vmcnt(0)
	v_readfirstlane_b32 s14, v3
	v_sub_u32_e32 v3, 0, v2
	v_rcp_iflag_f32_e32 v4, v4
	v_add_u32_e32 v5, s14, v1
	v_mul_f32_e32 v4, 0x4f7ffffe, v4
	v_cvt_u32_f32_e32 v4, v4
	v_mul_lo_u32 v1, v3, v4
	v_mul_hi_u32 v1, v4, v1
	v_add_u32_e32 v1, v4, v1
	v_mul_hi_u32 v1, v5, v1
	v_mul_lo_u32 v3, v1, v2
	v_sub_u32_e32 v3, v5, v3
	v_add_u32_e32 v4, 1, v1
	v_cmp_ge_u32_e32 vcc, v3, v2
	s_nop 1
	v_cndmask_b32_e32 v1, v1, v4, vcc
	v_sub_u32_e32 v4, v3, v2
	v_cndmask_b32_e32 v3, v3, v4, vcc
	v_add_u32_e32 v4, 1, v1
	v_cmp_ge_u32_e32 vcc, v3, v2
	v_add_u32_e32 v3, 1, v5
	s_nop 0
	v_cndmask_b32_e32 v1, v1, v4, vcc
	v_mul_lo_u32 v4, v2, v1
	v_add_u32_e32 v2, v4, v2
	v_cmp_ne_u32_e32 vcc, v3, v2
	s_and_saveexec_b64 s[14:15], vcc
	s_xor_b64 s[14:15], exec, s[14:15]
	s_cbranch_execz .LBB0_382
	s_waitcnt lgkmcnt(0)
	s_add_u32 s20, s86, 0x3500
	s_addc_u32 s21, s87, 0
	v_mov_b32_e32 v0, 0
	global_load_dword v0, v0, s[20:21] sc1
	s_waitcnt vmcnt(0)
	v_cmp_eq_u32_e32 vcc, v0, v1
	s_and_saveexec_b64 s[16:17], vcc
	s_cbranch_execz .LBB0_381
	s_add_u32 s18, s80, 0x60200
	s_addc_u32 s19, s81, 0
	s_mov_b32 s33, 1
	s_mov_b64 s[22:23], 0
	v_mov_b32_e32 v0, 0
	s_branch .LBB0_372

; __device__ __forceinline__ unsigned xb_ld(unsigned* p)              { return __hip_atomic_load(p, __ATOMIC_RELAXED, __HIP_MEMORY_SCOPE_AGENT); }
; __device__ __forceinline__ unsigned xb_add(unsigned* p, unsigned v) { return __hip_atomic_fetch_add(p, v, __ATOMIC_RELAXED, __HIP_MEMORY_SCOPE_AGENT); }
; #define XB_SPIN(cond, bar) do { unsigned _sp = 0; while (cond) { if (XB_SLEEP) __builtin_amdgcn_s_sleep(1); \
;     if ((++_sp & 255u) == 0u) { if (xb_ld(&(bar)[XB_TMO])) break; if (_sp > XB_SPIN_CAP) { atomicAdd(&(bar)[XB_TMO], 1u); break; } } } } while (0)
; __device__ __forceinline__ void xcd_barrier(const XcdBarrier& b) {
;     ...
;         const unsigned old = xb_add(&bar[XB_XSUB(b.x)], 1u);
;         const unsigned gen = old / nloc;
;         if (old + 1u == (gen + 1u) * nloc) {
;             __builtin_amdgcn_fence(__ATOMIC_RELEASE, "agent");
;             asm volatile("s_waitcnt vmcnt(0)" ::: "memory");
;             const unsigned og = xb_add(&bar[XB_TOP], 1u);
;             const unsigned tg = og / nx;
;             if (og + 1u == (tg + 1u) * nx) xb_add(&bar[XB_TOPGEN], 1u);
;             else XB_SPIN(xb_ld(&bar[XB_TOPGEN]) == tg, bar);
;             __builtin_amdgcn_fence(__ATOMIC_ACQUIRE, "agent");
;             xb_add(&bar[XB_XGEN(b.x)], 1u);
;             asm volatile("s_waitcnt vmcnt(0)" ::: "memory");
;         } else {
;             XB_SPIN(xb_ld(&bar[XB_XGEN(b.x)]) == gen, bar);
;             __builtin_amdgcn_fence(__ATOMIC_ACQUIRE, "agent");
;             asm volatile("s_waitcnt vmcnt(0)" ::: "memory");
.LBB0_474:
	s_or_b64 exec, exec, s[8:9]
	v_cvt_f32_u32_e32 v4, v2
	s_waitcnt vmcnt(0)
	v_readfirstlane_b32 s6, v3
	v_sub_u32_e32 v3, 0, v2
	v_rcp_iflag_f32_e32 v4, v4
	v_add_u32_e32 v5, s6, v1
	v_mul_f32_e32 v4, 0x4f7ffffe, v4
	v_cvt_u32_f32_e32 v4, v4
	v_mul_lo_u32 v1, v3, v4
	v_mul_hi_u32 v1, v4, v1
	v_add_u32_e32 v1, v4, v1
	v_mul_hi_u32 v1, v5, v1
	v_mul_lo_u32 v3, v1, v2
	v_sub_u32_e32 v3, v5, v3
	v_add_u32_e32 v4, 1, v1
	v_cmp_ge_u32_e32 vcc, v3, v2
	s_nop 1
	v_cndmask_b32_e32 v1, v1, v4, vcc
	v_sub_u32_e32 v4, v3, v2
	v_cndmask_b32_e32 v3, v3, v4, vcc
	v_add_u32_e32 v4, 1, v1
	v_cmp_ge_u32_e32 vcc, v3, v2
	v_add_u32_e32 v3, 1, v5
	s_nop 0
	v_cndmask_b32_e32 v1, v1, v4, vcc
	v_mul_lo_u32 v4, v2, v1
	v_add_u32_e32 v2, v4, v2
	v_cmp_ne_u32_e32 vcc, v3, v2
	s_and_saveexec_b64 s[6:7], vcc
	s_xor_b64 s[6:7], exec, s[6:7]
	s_cbranch_execz .LBB0_488
	s_waitcnt lgkmcnt(0)
	s_add_u32 s16, s86, 0x3500
	s_addc_u32 s17, s87, 0
	v_mov_b32_e32 v0, 0
	global_load_dword v0, v0, s[16:17] sc1
	s_waitcnt vmcnt(0)
	v_cmp_eq_u32_e32 vcc, v0, v1
	s_and_saveexec_b64 s[8:9], vcc
	s_cbranch_execz .LBB0_487
	s_add_u32 s10, s80, 0x60200
	s_addc_u32 s11, s81, 0
	s_mov_b32 s28, 1
	s_mov_b64 s[18:19], 0
	v_mov_b32_e32 v0, 0
	s_branch .LBB0_478

; __device__ __forceinline__ unsigned xb_ld(unsigned* p)              { return __hip_atomic_load(p, __ATOMIC_RELAXED, __HIP_MEMORY_SCOPE_AGENT); }
; __device__ __forceinline__ unsigned xb_add(unsigned* p, unsigned v) { return __hip_atomic_fetch_add(p, v, __ATOMIC_RELAXED, __HIP_MEMORY_SCOPE_AGENT); }
; #define XB_SPIN(cond, bar) do { unsigned _sp = 0; while (cond) { if (XB_SLEEP) __builtin_amdgcn_s_sleep(1); \
;     if ((++_sp & 255u) == 0u) { if (xb_ld(&(bar)[XB_TMO])) break; if (_sp > XB_SPIN_CAP) { atomicAdd(&(bar)[XB_TMO], 1u); break; } } } } while (0)
; __device__ __forceinline__ void xcd_barrier(const XcdBarrier& b) {
;     ...
;         const unsigned old = xb_add(&bar[XB_XSUB(b.x)], 1u);
;         const unsigned gen = old / nloc;
;         if (old + 1u == (gen + 1u) * nloc) {
;             __builtin_amdgcn_fence(__ATOMIC_RELEASE, "agent");
;             asm volatile("s_waitcnt vmcnt(0)" ::: "memory");
;             const unsigned og = xb_add(&bar[XB_TOP], 1u);
;             const unsigned tg = og / nx;
;             if (og + 1u == (tg + 1u) * nx) xb_add(&bar[XB_TOPGEN], 1u);
;             else XB_SPIN(xb_ld(&bar[XB_TOPGEN]) == tg, bar);
;             __builtin_amdgcn_fence(__ATOMIC_ACQUIRE, "agent");
;             xb_add(&bar[XB_XGEN(b.x)], 1u);
;             asm volatile("s_waitcnt vmcnt(0)" ::: "memory");
;         } else {
;             XB_SPIN(xb_ld(&bar[XB_XGEN(b.x)]) == gen, bar);
;             __builtin_amdgcn_fence(__ATOMIC_ACQUIRE, "agent");
;             asm volatile("s_waitcnt vmcnt(0)" ::: "memory");
.LBB0_645:
	s_or_b64 exec, exec, s[8:9]
	v_cvt_f32_u32_e32 v4, v2
	s_waitcnt vmcnt(0)
	v_readfirstlane_b32 s6, v3
	v_sub_u32_e32 v3, 0, v2
	v_rcp_iflag_f32_e32 v4, v4
	v_add_u32_e32 v5, s6, v1
	v_mul_f32_e32 v4, 0x4f7ffffe, v4
	v_cvt_u32_f32_e32 v4, v4
	v_mul_lo_u32 v1, v3, v4
	v_mul_hi_u32 v1, v4, v1
	v_add_u32_e32 v1, v4, v1
	v_mul_hi_u32 v1, v5, v1
	v_mul_lo_u32 v3, v1, v2
	v_sub_u32_e32 v3, v5, v3
	v_add_u32_e32 v4, 1, v1
	v_cmp_ge_u32_e32 vcc, v3, v2
	s_nop 1
	v_cndmask_b32_e32 v1, v1, v4, vcc
	v_sub_u32_e32 v4, v3, v2
	v_cndmask_b32_e32 v3, v3, v4, vcc
	v_add_u32_e32 v4, 1, v1
	v_cmp_ge_u32_e32 vcc, v3, v2
	v_add_u32_e32 v3, 1, v5
	s_nop 0
	v_cndmask_b32_e32 v1, v1, v4, vcc
	v_mul_lo_u32 v4, v2, v1
	v_add_u32_e32 v2, v4, v2
	v_cmp_ne_u32_e32 vcc, v3, v2
	s_and_saveexec_b64 s[6:7], vcc
	s_xor_b64 s[6:7], exec, s[6:7]
	s_cbranch_execz .LBB0_659
	s_waitcnt lgkmcnt(0)
	s_add_u32 s14, s86, 0x3500
	s_addc_u32 s15, s87, 0
	v_mov_b32_e32 v0, 0
	global_load_dword v0, v0, s[14:15] sc1
	s_waitcnt vmcnt(0)
	v_cmp_eq_u32_e32 vcc, v0, v1
	s_and_saveexec_b64 s[8:9], vcc
	s_cbranch_execz .LBB0_658
	s_add_u32 s10, s80, 0x60200
	s_addc_u32 s11, s81, 0
	s_mov_b32 s26, 1
	s_mov_b64 s[16:17], 0
	v_mov_b32_e32 v0, 0
	s_branch .LBB0_649

; __device__ __forceinline__ unsigned xb_ld(unsigned* p)              { return __hip_atomic_load(p, __ATOMIC_RELAXED, __HIP_MEMORY_SCOPE_AGENT); }
; __device__ __forceinline__ unsigned xb_add(unsigned* p, unsigned v) { return __hip_atomic_fetch_add(p, v, __ATOMIC_RELAXED, __HIP_MEMORY_SCOPE_AGENT); }
; #define XB_SPIN(cond, bar) do { unsigned _sp = 0; while (cond) { if (XB_SLEEP) __builtin_amdgcn_s_sleep(1); \
;     if ((++_sp & 255u) == 0u) { if (xb_ld(&(bar)[XB_TMO])) break; if (_sp > XB_SPIN_CAP) { atomicAdd(&(bar)[XB_TMO], 1u); break; } } } } while (0)
; __device__ __forceinline__ void xcd_barrier(const XcdBarrier& b) {
;     ...
;         const unsigned old = xb_add(&bar[XB_XSUB(b.x)], 1u);
;         const unsigned gen = old / nloc;
;         if (old + 1u == (gen + 1u) * nloc) {
;             __builtin_amdgcn_fence(__ATOMIC_RELEASE, "agent");
;             asm volatile("s_waitcnt vmcnt(0)" ::: "memory");
;             const unsigned og = xb_add(&bar[XB_TOP], 1u);
;             const unsigned tg = og / nx;
;             if (og + 1u == (tg + 1u) * nx) xb_add(&bar[XB_TOPGEN], 1u);
;             else XB_SPIN(xb_ld(&bar[XB_TOPGEN]) == tg, bar);
;             __builtin_amdgcn_fence(__ATOMIC_ACQUIRE, "agent");
;             xb_add(&bar[XB_XGEN(b.x)], 1u);
;             asm volatile("s_waitcnt vmcnt(0)" ::: "memory");
;         } else {
;             XB_SPIN(xb_ld(&bar[XB_XGEN(b.x)]) == gen, bar);
;             __builtin_amdgcn_fence(__ATOMIC_ACQUIRE, "agent");
;             asm volatile("s_waitcnt vmcnt(0)" ::: "memory");
.LBB0_830:
	s_or_b64 exec, exec, s[6:7]
	v_cvt_f32_u32_e32 v4, v2
	s_waitcnt vmcnt(0)
	v_readfirstlane_b32 s4, v3
	v_sub_u32_e32 v3, 0, v2
	v_rcp_iflag_f32_e32 v4, v4
	v_add_u32_e32 v5, s4, v1
	v_mul_f32_e32 v4, 0x4f7ffffe, v4
	v_cvt_u32_f32_e32 v4, v4
	v_mul_lo_u32 v1, v3, v4
	v_mul_hi_u32 v1, v4, v1
	v_add_u32_e32 v1, v4, v1
	v_mul_hi_u32 v1, v5, v1
	v_mul_lo_u32 v3, v1, v2
	v_sub_u32_e32 v3, v5, v3
	v_add_u32_e32 v4, 1, v1
	v_cmp_ge_u32_e32 vcc, v3, v2
	s_nop 1
	v_cndmask_b32_e32 v1, v1, v4, vcc
	v_sub_u32_e32 v4, v3, v2
	v_cndmask_b32_e32 v3, v3, v4, vcc
	v_add_u32_e32 v4, 1, v1
	v_cmp_ge_u32_e32 vcc, v3, v2
	v_add_u32_e32 v3, 1, v5
	s_nop 0
	v_cndmask_b32_e32 v1, v1, v4, vcc
	v_mul_lo_u32 v4, v2, v1
	v_add_u32_e32 v2, v4, v2
	v_cmp_ne_u32_e32 vcc, v3, v2
	s_and_saveexec_b64 s[4:5], vcc
	s_xor_b64 s[4:5], exec, s[4:5]
	s_cbranch_execz .LBB0_844
	s_waitcnt lgkmcnt(0)
	s_add_u32 s10, s80, 0x3500
	s_addc_u32 s11, s81, 0
	v_mov_b32_e32 v0, 0
	global_load_dword v0, v0, s[10:11] sc1
	s_waitcnt vmcnt(0)
	v_cmp_eq_u32_e32 vcc, v0, v1
	s_and_saveexec_b64 s[6:7], vcc
	s_cbranch_execz .LBB0_843
	s_add_u32 s8, s76, 0x60200
	s_addc_u32 s9, s77, 0
	s_mov_b32 s22, 1
	s_mov_b64 s[12:13], 0
	v_mov_b32_e32 v0, 0
	s_branch .LBB0_834

; __device__ __forceinline__ unsigned xb_ld(unsigned* p)              { return __hip_atomic_load(p, __ATOMIC_RELAXED, __HIP_MEMORY_SCOPE_AGENT); }
; __device__ __forceinline__ unsigned xb_add(unsigned* p, unsigned v) { return __hip_atomic_fetch_add(p, v, __ATOMIC_RELAXED, __HIP_MEMORY_SCOPE_AGENT); }
; #define XB_SPIN(cond, bar) do { unsigned _sp = 0; while (cond) { if (XB_SLEEP) __builtin_amdgcn_s_sleep(1); \
;     if ((++_sp & 255u) == 0u) { if (xb_ld(&(bar)[XB_TMO])) break; if (_sp > XB_SPIN_CAP) { atomicAdd(&(bar)[XB_TMO], 1u); break; } } } } while (0)
; __device__ __forceinline__ void xcd_barrier(const XcdBarrier& b) {
;     ...
;         const unsigned old = xb_add(&bar[XB_XSUB(b.x)], 1u);
;         const unsigned gen = old / nloc;
;         if (old + 1u == (gen + 1u) * nloc) {
;             __builtin_amdgcn_fence(__ATOMIC_RELEASE, "agent");
;             asm volatile("s_waitcnt vmcnt(0)" ::: "memory");
;             const unsigned og = xb_add(&bar[XB_TOP], 1u);
;             const unsigned tg = og / nx;
;             if (og + 1u == (tg + 1u) * nx) xb_add(&bar[XB_TOPGEN], 1u);
;             else XB_SPIN(xb_ld(&bar[XB_TOPGEN]) == tg, bar);
;             __builtin_amdgcn_fence(__ATOMIC_ACQUIRE, "agent");
;             xb_add(&bar[XB_XGEN(b.x)], 1u);
;             asm volatile("s_waitcnt vmcnt(0)" ::: "memory");
;         } else {
;             XB_SPIN(xb_ld(&bar[XB_XGEN(b.x)]) == gen, bar);
;             __builtin_amdgcn_fence(__ATOMIC_ACQUIRE, "agent");
;             asm volatile("s_waitcnt vmcnt(0)" ::: "memory");
.LBB0_995:
	s_or_b64 exec, exec, s[8:9]
	v_cvt_f32_u32_e32 v4, v2
	s_waitcnt vmcnt(0)
	v_readfirstlane_b32 s6, v3
	v_sub_u32_e32 v3, 0, v2
	v_rcp_iflag_f32_e32 v4, v4
	v_add_u32_e32 v5, s6, v1
	v_mul_f32_e32 v4, 0x4f7ffffe, v4
	v_cvt_u32_f32_e32 v4, v4
	v_mul_lo_u32 v1, v3, v4
	v_mul_hi_u32 v1, v4, v1
	v_add_u32_e32 v1, v4, v1
	v_mul_hi_u32 v1, v5, v1
	v_mul_lo_u32 v3, v1, v2
	v_sub_u32_e32 v3, v5, v3
	v_add_u32_e32 v4, 1, v1
	v_cmp_ge_u32_e32 vcc, v3, v2
	s_nop 1
	v_cndmask_b32_e32 v1, v1, v4, vcc
	v_sub_u32_e32 v4, v3, v2
	v_cndmask_b32_e32 v3, v3, v4, vcc
	v_add_u32_e32 v4, 1, v1
	v_cmp_ge_u32_e32 vcc, v3, v2
	v_add_u32_e32 v3, 1, v5
	s_nop 0
	v_cndmask_b32_e32 v1, v1, v4, vcc
	v_mul_lo_u32 v4, v2, v1
	v_add_u32_e32 v2, v4, v2
	v_cmp_ne_u32_e32 vcc, v3, v2
	s_and_saveexec_b64 s[6:7], vcc
	s_xor_b64 s[6:7], exec, s[6:7]
	s_cbranch_execz .LBB0_1009
	s_waitcnt lgkmcnt(0)
	s_add_u32 s12, s80, 0x3500
	s_addc_u32 s13, s81, 0
	v_mov_b32_e32 v0, 0
	global_load_dword v0, v0, s[12:13] sc1
	s_waitcnt vmcnt(0)
	v_cmp_eq_u32_e32 vcc, v0, v1
	s_and_saveexec_b64 s[8:9], vcc
	s_cbranch_execz .LBB0_1008
	s_add_u32 s10, s76, 0x60200
	s_addc_u32 s11, s77, 0
	s_mov_b32 s24, 1
	s_mov_b64 s[14:15], 0
	v_mov_b32_e32 v0, 0
	s_branch .LBB0_999

; __device__ __forceinline__ unsigned xb_ld(unsigned* p)              { return __hip_atomic_load(p, __ATOMIC_RELAXED, __HIP_MEMORY_SCOPE_AGENT); }
; __device__ __forceinline__ unsigned xb_add(unsigned* p, unsigned v) { return __hip_atomic_fetch_add(p, v, __ATOMIC_RELAXED, __HIP_MEMORY_SCOPE_AGENT); }
; #define XB_SPIN(cond, bar) do { unsigned _sp = 0; while (cond) { if (XB_SLEEP) __builtin_amdgcn_s_sleep(1); \
;     if ((++_sp & 255u) == 0u) { if (xb_ld(&(bar)[XB_TMO])) break; if (_sp > XB_SPIN_CAP) { atomicAdd(&(bar)[XB_TMO], 1u); break; } } } } while (0)
; __device__ __forceinline__ void xcd_barrier(const XcdBarrier& b) {
;     ...
;         const unsigned old = xb_add(&bar[XB_XSUB(b.x)], 1u);
;         const unsigned gen = old / nloc;
;         if (old + 1u == (gen + 1u) * nloc) {
;             __builtin_amdgcn_fence(__ATOMIC_RELEASE, "agent");
;             asm volatile("s_waitcnt vmcnt(0)" ::: "memory");
;             const unsigned og = xb_add(&bar[XB_TOP], 1u);
;             const unsigned tg = og / nx;
;             if (og + 1u == (tg + 1u) * nx) xb_add(&bar[XB_TOPGEN], 1u);
;             else XB_SPIN(xb_ld(&bar[XB_TOPGEN]) == tg, bar);
;             __builtin_amdgcn_fence(__ATOMIC_ACQUIRE, "agent");
;             xb_add(&bar[XB_XGEN(b.x)], 1u);
;             asm volatile("s_waitcnt vmcnt(0)" ::: "memory");
;         } else {
;             XB_SPIN(xb_ld(&bar[XB_XGEN(b.x)]) == gen, bar);
;             __builtin_amdgcn_fence(__ATOMIC_ACQUIRE, "agent");
;             asm volatile("s_waitcnt vmcnt(0)" ::: "memory");
.LBB0_1160:
	s_or_b64 exec, exec, s[8:9]
	v_cvt_f32_u32_e32 v4, v2
	s_waitcnt vmcnt(0)
	v_readfirstlane_b32 s4, v3
	v_sub_u32_e32 v3, 0, v2
	v_rcp_iflag_f32_e32 v4, v4
	v_add_u32_e32 v5, s4, v1
	v_mul_f32_e32 v4, 0x4f7ffffe, v4
	v_cvt_u32_f32_e32 v4, v4
	v_mul_lo_u32 v1, v3, v4
	v_mul_hi_u32 v1, v4, v1
	v_add_u32_e32 v1, v4, v1
	v_mul_hi_u32 v1, v5, v1
	v_mul_lo_u32 v3, v1, v2
	v_sub_u32_e32 v3, v5, v3
	v_add_u32_e32 v4, 1, v1
	v_cmp_ge_u32_e32 vcc, v3, v2
	s_nop 1
	v_cndmask_b32_e32 v1, v1, v4, vcc
	v_sub_u32_e32 v4, v3, v2
	v_cndmask_b32_e32 v3, v3, v4, vcc
	v_add_u32_e32 v4, 1, v1
	v_cmp_ge_u32_e32 vcc, v3, v2
	v_add_u32_e32 v3, 1, v5
	s_nop 0
	v_cndmask_b32_e32 v1, v1, v4, vcc
	v_mul_lo_u32 v4, v2, v1
	v_add_u32_e32 v2, v4, v2
	v_cmp_ne_u32_e32 vcc, v3, v2
	s_and_saveexec_b64 s[4:5], vcc
	s_xor_b64 s[4:5], exec, s[4:5]
	s_cbranch_execz .LBB0_1174
	s_waitcnt lgkmcnt(0)
	s_add_u32 s12, s80, 0x3500
	s_addc_u32 s13, s81, 0
	v_mov_b32_e32 v0, 0
	global_load_dword v0, v0, s[12:13] sc1
	s_waitcnt vmcnt(0)
	v_cmp_eq_u32_e32 vcc, v0, v1
	s_and_saveexec_b64 s[8:9], vcc
	s_cbranch_execz .LBB0_1173
	s_add_u32 s10, s76, 0x60200
	s_addc_u32 s11, s77, 0
	s_mov_b32 s24, 1
	s_mov_b64 s[14:15], 0
	v_mov_b32_e32 v0, 0
	s_branch .LBB0_1164
